# mix2 O=QC section hand-written: xor-add addressing with immediate offsets (2 VALU instead of 10 per column block), next block's LDS reads issued between the current block's MFMAs
# speedup vs baseline: 1.0114x; 1.0114x over previous
; #define TRFRAG(img, c, ks) trfrag_(lds, (img) + 256u * (32u * (ks)) + TRA(c, 0), (img) + 256u * (32u * (ks) + 4u) + TRA(c, 1))
; #define MFMA16(a, b, c) __builtin_amdgcn_mfma_f32_16x16x32_bf16((a), (b), (c), 0, 0, 0)
; __device__ void mix_sweep(const Params& P, LAS unsigned char* lds, int tok0, int pos0, int seqlen, int hd, int dir, bool state_only, bool final_pass,
;                           f32x4 (&Cacc)[9], float& m_state, float& aseg_sum, float lgam) {
;     ...
;         const float decay = vsc[0];
;         if (!state_only) {
;             int irow = 16 * w + fr; asm volatile("" : "+v"(irow));
;             bf16x8 qf[4];
; #pragma unroll
;             for (int s = 0; s < 4; ++s) qf[s] = ROWFRAG(IMG_Q, 16 * w, s);
;             f32x4 O[9];
;             __builtin_amdgcn_s_setprio(1);
; #pragma unroll
;             for (int nt = 0; nt < 8; ++nt) { f32x4 a = (f32x4){0.f, 0.f, 0.f, 0.f}; LAUNDER_L16
;                 bf16x8 cf[4];
; #pragma unroll
;                 for (int ks = 0; ks < 4; ++ks) cf[ks] = TRFRAG(IMG_C, nt, ks);
;                 __builtin_amdgcn_sched_barrier(0);
; #pragma unroll
;                 for (int ks = 0; ks < 4; ++ks) a = MFMA16(cf[ks], qf[ks], a);
;                 O[nt] = a; }
.LBB0_105:
	v_mov_b32_e32 v0, s29
	s_waitcnt lgkmcnt(0)
	s_barrier
	ds_read_b32 v156, v0
	v_mov_b32_e32 v188, v219
	v_add_u32_e32 v0, s84, v174
	v_add_u32_e32 v159, s84, v176
	v_add_u32_e32 v157, s84, v175
	ds_read_b128 v[92:95], v0
	ds_read_b128 v[96:99], v157
	v_add_u32_e32 v170, s84, v177
	ds_read_b128 v[100:103], v159
	ds_read_b128 v[88:91], v170
	s_setprio 1
	v_add_u32_e32 v204, v193, v178
	v_xad_u32 v205, v178, 16, v193
	ds_read_b64_tr_b16 v[222:223], v204
	ds_read_b64_tr_b16 v[224:225], v205 offset:1024
	ds_read_b64_tr_b16 v[226:227], v204 offset:8192
	ds_read_b64_tr_b16 v[228:229], v205 offset:9216
	ds_read_b64_tr_b16 v[230:231], v204 offset:16384
	ds_read_b64_tr_b16 v[232:233], v205 offset:17408
	ds_read_b64_tr_b16 v[234:235], v204 offset:24576
	ds_read_b64_tr_b16 v[236:237], v205 offset:25600
	v_xad_u32 v206, v178, 32, v193
	v_xad_u32 v207, v178, 48, v193
	s_waitcnt lgkmcnt(6)
	v_mfma_f32_16x16x32_bf16 v[76:79], v[222:225], v[92:95], 0
	ds_read_b64_tr_b16 v[238:239], v206
	ds_read_b64_tr_b16 v[240:241], v207 offset:1024
	ds_read_b64_tr_b16 v[242:243], v206 offset:8192
	ds_read_b64_tr_b16 v[244:245], v207 offset:9216
	s_waitcnt lgkmcnt(8)
	v_mfma_f32_16x16x32_bf16 v[76:79], v[226:229], v[96:99], v[76:79]
	ds_read_b64_tr_b16 v[124:125], v206 offset:16384
	ds_read_b64_tr_b16 v[126:127], v207 offset:17408
	ds_read_b64_tr_b16 v[128:129], v206 offset:24576
	ds_read_b64_tr_b16 v[130:131], v207 offset:25600
	s_waitcnt lgkmcnt(10)
	v_mfma_f32_16x16x32_bf16 v[76:79], v[230:233], v[100:103], v[76:79]
	s_waitcnt lgkmcnt(8)
	v_mfma_f32_16x16x32_bf16 v[76:79], v[234:237], v[88:91], v[76:79]
	v_xad_u32 v204, v178, 64, v193
	s_movk_i32 s15, 0x50
	v_xad_u32 v205, v178, s15, v193
	s_waitcnt lgkmcnt(6)
	v_mfma_f32_16x16x32_bf16 v[80:83], v[238:241], v[92:95], 0
	ds_read_b64_tr_b16 v[222:223], v204
	ds_read_b64_tr_b16 v[224:225], v205 offset:1024
	ds_read_b64_tr_b16 v[226:227], v204 offset:8192
	ds_read_b64_tr_b16 v[228:229], v205 offset:9216
	s_waitcnt lgkmcnt(8)
	v_mfma_f32_16x16x32_bf16 v[80:83], v[242:245], v[96:99], v[80:83]
	ds_read_b64_tr_b16 v[230:231], v204 offset:16384
	ds_read_b64_tr_b16 v[232:233], v205 offset:17408
	ds_read_b64_tr_b16 v[234:235], v204 offset:24576
	ds_read_b64_tr_b16 v[236:237], v205 offset:25600
	s_waitcnt lgkmcnt(10)
	v_mfma_f32_16x16x32_bf16 v[80:83], v[124:127], v[100:103], v[80:83]
	s_waitcnt lgkmcnt(8)
	v_mfma_f32_16x16x32_bf16 v[80:83], v[128:131], v[88:91], v[80:83]
	s_movk_i32 s15, 0x60
	v_xad_u32 v206, v178, s15, v193
	s_movk_i32 s15, 0x70
	v_xad_u32 v207, v178, s15, v193
	s_waitcnt lgkmcnt(6)
	v_mfma_f32_16x16x32_bf16 v[84:87], v[222:225], v[92:95], 0
	ds_read_b64_tr_b16 v[238:239], v206
	ds_read_b64_tr_b16 v[240:241], v207 offset:1024
	ds_read_b64_tr_b16 v[242:243], v206 offset:8192
	ds_read_b64_tr_b16 v[244:245], v207 offset:9216
	s_waitcnt lgkmcnt(8)
	v_mfma_f32_16x16x32_bf16 v[84:87], v[226:229], v[96:99], v[84:87]
	ds_read_b64_tr_b16 v[124:125], v206 offset:16384
	ds_read_b64_tr_b16 v[126:127], v207 offset:17408
	ds_read_b64_tr_b16 v[128:129], v206 offset:24576
	ds_read_b64_tr_b16 v[130:131], v207 offset:25600
	s_waitcnt lgkmcnt(10)
	v_mfma_f32_16x16x32_bf16 v[84:87], v[230:233], v[100:103], v[84:87]
	s_waitcnt lgkmcnt(8)
	v_mfma_f32_16x16x32_bf16 v[84:87], v[234:237], v[88:91], v[84:87]
	s_movk_i32 s15, 0x80
	v_xad_u32 v204, v178, s15, v193
	s_movk_i32 s15, 0x90
	v_xad_u32 v205, v178, s15, v193
	s_waitcnt lgkmcnt(6)
	v_mfma_f32_16x16x32_bf16 v[104:107], v[238:241], v[92:95], 0
	ds_read_b64_tr_b16 v[222:223], v204
	ds_read_b64_tr_b16 v[224:225], v205 offset:1024
	ds_read_b64_tr_b16 v[226:227], v204 offset:8192
	ds_read_b64_tr_b16 v[228:229], v205 offset:9216
	s_waitcnt lgkmcnt(8)
	v_mfma_f32_16x16x32_bf16 v[104:107], v[242:245], v[96:99], v[104:107]
	ds_read_b64_tr_b16 v[230:231], v204 offset:16384
	ds_read_b64_tr_b16 v[232:233], v205 offset:17408
	ds_read_b64_tr_b16 v[234:235], v204 offset:24576
	ds_read_b64_tr_b16 v[236:237], v205 offset:25600
	s_waitcnt lgkmcnt(10)
	v_mfma_f32_16x16x32_bf16 v[104:107], v[124:127], v[100:103], v[104:107]
	s_waitcnt lgkmcnt(8)
; #define TRFRAG(img, c, ks) trfrag_(lds, (img) + 256u * (32u * (ks)) + TRA(c, 0), (img) + 256u * (32u * (ks) + 4u) + TRA(c, 1))
; #define TRFRAGX(img, ks) trfrag_(lds, (img) + 32u * (32u * (ks)) + FB.txb, (img) + 32u * (32u * (ks) + 4u) + FB.txb)
; #define MFMA16(a, b, c) __builtin_amdgcn_mfma_f32_16x16x32_bf16((a), (b), (c), 0, 0, 0)
; __device__ void mix_sweep(const Params& P, LAS unsigned char* lds, int tok0, int pos0, int seqlen, int hd, int dir, bool state_only, bool final_pass,
;                           f32x4 (&Cacc)[9], float& m_state, float& aseg_sum, float lgam) {
;     ...
;             for (int nt = 0; nt < 8; ++nt) { f32x4 a = (f32x4){0.f, 0.f, 0.f, 0.f}; LAUNDER_L16
;                 bf16x8 cf[4];
; #pragma unroll
;                 for (int ks = 0; ks < 4; ++ks) cf[ks] = TRFRAG(IMG_C, nt, ks);
;                 __builtin_amdgcn_sched_barrier(0);
; #pragma unroll
;                 for (int ks = 0; ks < 4; ++ks) a = MFMA16(cf[ks], qf[ks], a);
;                 O[nt] = a; }
;             { f32x4 a = (f32x4){0.f, 0.f, 0.f, 0.f};
;               if (is_m) {
; #pragma unroll
;                   for (int ks = 0; ks < 4; ++ks) a = MFMA16(TRFRAGX(IMG_CX, ks), qf[ks], a); }
;               O[8] = a; }
	v_mfma_f32_16x16x32_bf16 v[104:107], v[128:131], v[88:91], v[104:107]
	s_movk_i32 s15, 0xa0
	v_xad_u32 v206, v178, s15, v193
	s_movk_i32 s15, 0xb0
	v_xad_u32 v207, v178, s15, v193
	s_waitcnt lgkmcnt(6)
	v_mfma_f32_16x16x32_bf16 v[108:111], v[222:225], v[92:95], 0
	ds_read_b64_tr_b16 v[238:239], v206
	ds_read_b64_tr_b16 v[240:241], v207 offset:1024
	ds_read_b64_tr_b16 v[242:243], v206 offset:8192
	ds_read_b64_tr_b16 v[244:245], v207 offset:9216
	s_waitcnt lgkmcnt(8)
	v_mfma_f32_16x16x32_bf16 v[108:111], v[226:229], v[96:99], v[108:111]
	ds_read_b64_tr_b16 v[124:125], v206 offset:16384
	ds_read_b64_tr_b16 v[126:127], v207 offset:17408
	ds_read_b64_tr_b16 v[128:129], v206 offset:24576
	ds_read_b64_tr_b16 v[130:131], v207 offset:25600
	s_waitcnt lgkmcnt(10)
	v_mfma_f32_16x16x32_bf16 v[108:111], v[230:233], v[100:103], v[108:111]
	s_waitcnt lgkmcnt(8)
	v_mfma_f32_16x16x32_bf16 v[108:111], v[234:237], v[88:91], v[108:111]
	s_movk_i32 s15, 0xc0
	v_xad_u32 v204, v178, s15, v193
	s_movk_i32 s15, 0xd0
	v_xad_u32 v205, v178, s15, v193
	s_waitcnt lgkmcnt(6)
	v_mfma_f32_16x16x32_bf16 v[112:115], v[238:241], v[92:95], 0
	ds_read_b64_tr_b16 v[222:223], v204
	ds_read_b64_tr_b16 v[224:225], v205 offset:1024
	ds_read_b64_tr_b16 v[226:227], v204 offset:8192
	ds_read_b64_tr_b16 v[228:229], v205 offset:9216
	s_waitcnt lgkmcnt(8)
	v_mfma_f32_16x16x32_bf16 v[112:115], v[242:245], v[96:99], v[112:115]
	ds_read_b64_tr_b16 v[230:231], v204 offset:16384
	ds_read_b64_tr_b16 v[232:233], v205 offset:17408
	ds_read_b64_tr_b16 v[234:235], v204 offset:24576
	ds_read_b64_tr_b16 v[236:237], v205 offset:25600
	s_waitcnt lgkmcnt(10)
	v_mfma_f32_16x16x32_bf16 v[112:115], v[124:127], v[100:103], v[112:115]
	s_waitcnt lgkmcnt(8)
	v_mfma_f32_16x16x32_bf16 v[112:115], v[128:131], v[88:91], v[112:115]
	s_movk_i32 s15, 0xe0
	v_xad_u32 v206, v178, s15, v193
	s_movk_i32 s15, 0xf0
	v_xad_u32 v207, v178, s15, v193
	s_waitcnt lgkmcnt(6)
	v_mfma_f32_16x16x32_bf16 v[116:119], v[222:225], v[92:95], 0
	ds_read_b64_tr_b16 v[238:239], v206
	ds_read_b64_tr_b16 v[240:241], v207 offset:1024
	ds_read_b64_tr_b16 v[242:243], v206 offset:8192
	ds_read_b64_tr_b16 v[244:245], v207 offset:9216
	s_waitcnt lgkmcnt(8)
	v_mfma_f32_16x16x32_bf16 v[116:119], v[226:229], v[96:99], v[116:119]
	ds_read_b64_tr_b16 v[124:125], v206 offset:16384
	ds_read_b64_tr_b16 v[126:127], v207 offset:17408
	ds_read_b64_tr_b16 v[128:129], v206 offset:24576
	ds_read_b64_tr_b16 v[130:131], v207 offset:25600
	s_waitcnt lgkmcnt(10)
	v_mfma_f32_16x16x32_bf16 v[116:119], v[230:233], v[100:103], v[116:119]
	s_waitcnt lgkmcnt(8)
	v_mfma_f32_16x16x32_bf16 v[116:119], v[234:237], v[88:91], v[116:119]
	s_waitcnt lgkmcnt(6)
	v_mfma_f32_16x16x32_bf16 v[120:123], v[238:241], v[92:95], 0
	s_waitcnt lgkmcnt(4)
	v_mfma_f32_16x16x32_bf16 v[120:123], v[242:245], v[96:99], v[120:123]
	s_waitcnt lgkmcnt(2)
	v_mfma_f32_16x16x32_bf16 v[120:123], v[124:127], v[100:103], v[120:123]
	s_waitcnt lgkmcnt(0)
	v_mfma_f32_16x16x32_bf16 v[120:123], v[128:131], v[88:91], v[120:123]
	s_and_b64 vcc, exec, s[48:49]
	v_mov_b32_e32 v72, 0
	v_mov_b32_e32 v73, 0
	v_mov_b32_e32 v74, 0
	v_mov_b32_e32 v75, 0
	s_cbranch_vccnz .LBB0_107
	v_add_u32_e32 v72, 0x21000, v167
	v_add_u32_e32 v74, 0x21080, v167
	ds_read_b64_tr_b16 v[72:73], v72
	ds_read_b64_tr_b16 v[74:75], v74
	v_add_u32_e32 v124, 0x21400, v167
	v_add_u32_e32 v126, 0x21480, v167
	ds_read_b64_tr_b16 v[124:125], v124
	ds_read_b64_tr_b16 v[126:127], v126
	s_waitcnt lgkmcnt(2)
	v_mfma_f32_16x16x32_bf16 v[72:75], v[72:75], v[92:95], 0
	s_waitcnt lgkmcnt(0)
	v_mfma_f32_16x16x32_bf16 v[72:75], v[124:127], v[96:99], v[72:75]
	v_add_u32_e32 v124, 0x21800, v167
	v_add_u32_e32 v126, 0x21880, v167
	ds_read_b64_tr_b16 v[124:125], v124
	ds_read_b64_tr_b16 v[126:127], v126
	s_waitcnt lgkmcnt(0)
	v_mfma_f32_16x16x32_bf16 v[72:75], v[124:127], v[100:103], v[72:75]
	v_add_u32_e32 v124, 0x21c00, v167
	v_add_u32_e32 v126, 0x21c80, v167
	ds_read_b64_tr_b16 v[124:125], v124
	ds_read_b64_tr_b16 v[126:127], v126
	s_waitcnt lgkmcnt(0)
	v_mfma_f32_16x16x32_bf16 v[72:75], v[124:127], v[88:91], v[72:75]
